# GEMM mainloops (in-proj and out-proj) rewritten: LDS-DMA global_load_lds into XOR-swizzled LDS, no register staging; pipelined indexer key load
# speedup vs baseline: 1.1546x; 1.0670x over previous
.LBB0_203:
	s_cmp_lt_i32 s24, 0
	s_cbranch_scc1 .LBB0_219
	s_lshr_b32 s4, s24, 3
	s_mul_hi_u32 s4, s4, 0x97b425f
	s_mul_i32 s5, s4, 0xd8
	s_sub_i32 s8, s24, s5
	s_lshl_b32 s5, s37, 4
	s_lshl_b32 s4, s4, 3
	s_add_i32 s4, s4, s5
	s_and_b32 s5, s8, 7
	s_or_b32 s4, s4, s5
	s_lshl_b32 s48, s4, 7
	s_lshl_b32 s4, s8, 4
	v_or_b32_e32 v100, s48, v214
	s_and_b32 s6, s4, 0xf80
	v_readfirstlane_b32 s4, v104
	s_and_b32 s49, s4, 64
	s_lshr_b32 s7, s4, 1
	s_and_b32 s50, s7, 0x7fffffc0
	s_lshr_b32 s7, s4, 6
	s_lshl_b32 s7, s7, 10
	v_bfe_u32 v217, v108, 1, 3
	v_lshlrev_b32_e32 v217, 4, v217
	v_xor_b32_e32 v217, v217, v110
	v_or_b32_e32 v218, s50, v108
	v_lshl_add_u32 v144, v218, 7, v217
	v_xor_b32_e32 v218, 64, v144
	v_or_b32_e32 v219, s49, v108
	v_lshl_add_u32 v100, v219, 7, v217
	v_xor_b32_e32 v219, 64, v100
	v_bfe_u32 v64, v214, 1, 3
	v_xor_b32_e32 v64, v64, v102
	v_lshlrev_b32_e32 v64, 4, v64
	v_lshl_add_u32 v64, v214, 11, v64
	v_add_u32_e32 v65, 0x10000, v64
	v_add_u32_e32 v66, 0x20000, v64
	v_add_u32_e32 v67, 0x30000, v64
	s_lshl_b32 s12, s48, 11
	s_add_u32 s4, s90, s12
	s_addc_u32 s5, s91, 0
	s_lshl_b32 s12, s6, 11
	s_add_u32 s24, s92, s12
	s_addc_u32 s25, s93, 0
	s_add_u32 m0, s7, 0x0
	s_nop 0
	global_load_lds_dwordx4 v64, s[4:5]
	s_add_u32 m0, s7, 0x1000
	s_nop 0
	global_load_lds_dwordx4 v65, s[4:5]
	s_add_u32 m0, s7, 0x2000
	s_nop 0
	global_load_lds_dwordx4 v66, s[4:5]
	s_add_u32 m0, s7, 0x3000
	s_nop 0
	global_load_lds_dwordx4 v67, s[4:5]
	s_add_u32 m0, s7, 0x9000
	s_nop 0
	global_load_lds_dwordx4 v64, s[24:25]
	s_add_u32 m0, s7, 0xa000
	s_nop 0
	global_load_lds_dwordx4 v65, s[24:25]
	s_add_u32 m0, s7, 0xb000
	s_nop 0
	global_load_lds_dwordx4 v66, s[24:25]
	s_add_u32 m0, s7, 0xc000
	s_nop 0
	global_load_lds_dwordx4 v67, s[24:25]
	s_add_u32 s4, s4, 0x80
	s_addc_u32 s5, s5, 0
	s_add_u32 s24, s24, 0x80
	s_addc_u32 s25, s25, 0
	v_mov_b64_e32 v[0:1], 0
	v_mov_b64_e32 v[2:3], 0
	v_mov_b64_e32 v[4:5], 0
	v_mov_b64_e32 v[6:7], 0
	v_mov_b64_e32 v[8:9], 0
	v_mov_b64_e32 v[10:11], 0
	v_mov_b64_e32 v[12:13], 0
	v_mov_b64_e32 v[14:15], 0
	v_mov_b64_e32 v[16:17], 0
	v_mov_b64_e32 v[18:19], 0
	v_mov_b64_e32 v[20:21], 0
	v_mov_b64_e32 v[22:23], 0
	v_mov_b64_e32 v[24:25], 0
	v_mov_b64_e32 v[26:27], 0
	v_mov_b64_e32 v[28:29], 0
	v_mov_b64_e32 v[30:31], 0
	v_mov_b64_e32 v[32:33], 0
	v_mov_b64_e32 v[34:35], 0
	v_mov_b64_e32 v[36:37], 0
	v_mov_b64_e32 v[38:39], 0
	v_mov_b64_e32 v[40:41], 0
	v_mov_b64_e32 v[42:43], 0
	v_mov_b64_e32 v[44:45], 0
	v_mov_b64_e32 v[46:47], 0
	v_mov_b64_e32 v[48:49], 0
	v_mov_b64_e32 v[50:51], 0
	v_mov_b64_e32 v[52:53], 0
	v_mov_b64_e32 v[54:55], 0
	v_mov_b64_e32 v[56:57], 0
	v_mov_b64_e32 v[58:59], 0
	v_mov_b64_e32 v[60:61], 0
	v_mov_b64_e32 v[62:63], 0
	s_mov_b32 s9, 0
	s_waitcnt vmcnt(0)
	s_barrier
.Lg1_loop:
	s_add_u32 m0, s7, 0x4800
	s_nop 0
	global_load_lds_dwordx4 v64, s[4:5]
	s_add_u32 m0, s7, 0x5800
	s_nop 0
	global_load_lds_dwordx4 v65, s[4:5]
	s_add_u32 m0, s7, 0x6800
	s_nop 0
	global_load_lds_dwordx4 v66, s[4:5]
	s_add_u32 m0, s7, 0x7800
	s_nop 0
	global_load_lds_dwordx4 v67, s[4:5]
	s_add_u32 m0, s7, 0xd800
	s_nop 0
	global_load_lds_dwordx4 v64, s[24:25]
	s_add_u32 m0, s7, 0xe800
	s_nop 0
	global_load_lds_dwordx4 v65, s[24:25]
	s_add_u32 m0, s7, 0xf800
	s_nop 0
	global_load_lds_dwordx4 v66, s[24:25]
	s_add_u32 m0, s7, 0x10800
	s_nop 0
	global_load_lds_dwordx4 v67, s[24:25]
	s_add_u32 s4, s4, 0x80
	s_addc_u32 s5, s5, 0
	s_add_u32 s24, s24, 0x80
	s_addc_u32 s25, s25, 0
	ds_read_b128 v[68:71], v144 offset:0
	ds_read_b128 v[84:87], v100 offset:36864
	ds_read_b128 v[88:91], v100 offset:38912
	ds_read_b128 v[92:95], v100 offset:40960
	ds_read_b128 v[158:161], v100 offset:43008
	ds_read_b128 v[72:75], v144 offset:2048
	ds_read_b128 v[76:79], v144 offset:4096
	ds_read_b128 v[80:83], v144 offset:6144
	s_waitcnt lgkmcnt(6)
	v_mfma_f32_16x16x32_bf16 v[44:47], v[68:71], v[84:87], v[44:47]
	ds_read_b128 v[162:165], v218 offset:0
	ds_read_b128 v[178:181], v219 offset:36864
	s_waitcnt lgkmcnt(7)
	v_mfma_f32_16x16x32_bf16 v[52:55], v[68:71], v[88:91], v[52:55]
	ds_read_b128 v[182:185], v219 offset:38912
	ds_read_b128 v[186:189], v219 offset:40960
	s_waitcnt lgkmcnt(8)
	v_mfma_f32_16x16x32_bf16 v[60:63], v[68:71], v[92:95], v[60:63]
	ds_read_b128 v[190:193], v219 offset:43008
	ds_read_b128 v[166:169], v218 offset:2048
	s_waitcnt lgkmcnt(9)
	v_mfma_f32_16x16x32_bf16 v[56:59], v[68:71], v[158:161], v[56:59]
	ds_read_b128 v[170:173], v218 offset:4096
	s_waitcnt lgkmcnt(9)
	v_mfma_f32_16x16x32_bf16 v[40:43], v[72:75], v[84:87], v[40:43]
	v_mfma_f32_16x16x32_bf16 v[36:39], v[72:75], v[88:91], v[36:39]
	v_mfma_f32_16x16x32_bf16 v[32:35], v[72:75], v[92:95], v[32:35]
	v_mfma_f32_16x16x32_bf16 v[28:31], v[72:75], v[158:161], v[28:31]
	ds_read_b128 v[174:177], v218 offset:6144
	s_waitcnt lgkmcnt(9)
	v_mfma_f32_16x16x32_bf16 v[24:27], v[76:79], v[84:87], v[24:27]
	v_mfma_f32_16x16x32_bf16 v[20:23], v[76:79], v[88:91], v[20:23]
	v_mfma_f32_16x16x32_bf16 v[16:19], v[76:79], v[92:95], v[16:19]
	v_mfma_f32_16x16x32_bf16 v[12:15], v[76:79], v[158:161], v[12:15]
	s_waitcnt lgkmcnt(8)
	v_mfma_f32_16x16x32_bf16 v[8:11], v[80:83], v[84:87], v[8:11]
	v_mfma_f32_16x16x32_bf16 v[4:7], v[80:83], v[88:91], v[4:7]
	v_mfma_f32_16x16x32_bf16 v[0:3], v[80:83], v[92:95], v[0:3]
	v_mfma_f32_16x16x32_bf16 v[48:51], v[80:83], v[158:161], v[48:51]
	s_waitcnt lgkmcnt(6)
	v_mfma_f32_16x16x32_bf16 v[44:47], v[162:165], v[178:181], v[44:47]
	s_waitcnt lgkmcnt(5)
	v_mfma_f32_16x16x32_bf16 v[52:55], v[162:165], v[182:185], v[52:55]
	s_waitcnt lgkmcnt(4)
	v_mfma_f32_16x16x32_bf16 v[60:63], v[162:165], v[186:189], v[60:63]
	s_waitcnt lgkmcnt(3)
	v_mfma_f32_16x16x32_bf16 v[56:59], v[162:165], v[190:193], v[56:59]
	s_waitcnt lgkmcnt(2)
	v_mfma_f32_16x16x32_bf16 v[40:43], v[166:169], v[178:181], v[40:43]
	v_mfma_f32_16x16x32_bf16 v[36:39], v[166:169], v[182:185], v[36:39]
	v_mfma_f32_16x16x32_bf16 v[32:35], v[166:169], v[186:189], v[32:35]
	v_mfma_f32_16x16x32_bf16 v[28:31], v[166:169], v[190:193], v[28:31]
	s_waitcnt lgkmcnt(1)
	v_mfma_f32_16x16x32_bf16 v[24:27], v[170:173], v[178:181], v[24:27]
	v_mfma_f32_16x16x32_bf16 v[20:23], v[170:173], v[182:185], v[20:23]
	v_mfma_f32_16x16x32_bf16 v[16:19], v[170:173], v[186:189], v[16:19]
	v_mfma_f32_16x16x32_bf16 v[12:15], v[170:173], v[190:193], v[12:15]
	s_waitcnt lgkmcnt(0)
	v_mfma_f32_16x16x32_bf16 v[8:11], v[174:177], v[178:181], v[8:11]
	v_mfma_f32_16x16x32_bf16 v[4:7], v[174:177], v[182:185], v[4:7]
	v_mfma_f32_16x16x32_bf16 v[0:3], v[174:177], v[186:189], v[0:3]
	v_mfma_f32_16x16x32_bf16 v[48:51], v[174:177], v[190:193], v[48:51]
	s_waitcnt vmcnt(0)
	s_barrier
	s_cmp_eq_u32 s9, 7
	s_cbranch_scc1 .Lg1_skip
	s_add_u32 m0, s7, 0x0
	s_nop 0
	global_load_lds_dwordx4 v64, s[4:5]
	s_add_u32 m0, s7, 0x1000
	s_nop 0
	global_load_lds_dwordx4 v65, s[4:5]
	s_add_u32 m0, s7, 0x2000
	s_nop 0
	global_load_lds_dwordx4 v66, s[4:5]
	s_add_u32 m0, s7, 0x3000
	s_nop 0
	global_load_lds_dwordx4 v67, s[4:5]
	s_add_u32 m0, s7, 0x9000
	s_nop 0
	global_load_lds_dwordx4 v64, s[24:25]
	s_add_u32 m0, s7, 0xa000
	s_nop 0
	global_load_lds_dwordx4 v65, s[24:25]
	s_add_u32 m0, s7, 0xb000
	s_nop 0
	global_load_lds_dwordx4 v66, s[24:25]
	s_add_u32 m0, s7, 0xc000
	s_nop 0
	global_load_lds_dwordx4 v67, s[24:25]
	s_add_u32 s4, s4, 0x80
	s_addc_u32 s5, s5, 0
	s_add_u32 s24, s24, 0x80
	s_addc_u32 s25, s25, 0
.Lg1_skip:
	ds_read_b128 v[68:71], v144 offset:18432
	ds_read_b128 v[84:87], v100 offset:55296
	ds_read_b128 v[88:91], v100 offset:57344
	ds_read_b128 v[92:95], v100 offset:59392
	ds_read_b128 v[158:161], v100 offset:61440
	ds_read_b128 v[72:75], v144 offset:20480
	ds_read_b128 v[76:79], v144 offset:22528
	ds_read_b128 v[80:83], v144 offset:24576
	s_waitcnt lgkmcnt(6)
	v_mfma_f32_16x16x32_bf16 v[44:47], v[68:71], v[84:87], v[44:47]
	ds_read_b128 v[162:165], v218 offset:18432
	ds_read_b128 v[178:181], v219 offset:55296
	s_waitcnt lgkmcnt(7)
	v_mfma_f32_16x16x32_bf16 v[52:55], v[68:71], v[88:91], v[52:55]
	ds_read_b128 v[182:185], v219 offset:57344
	ds_read_b128 v[186:189], v219 offset:59392
	s_waitcnt lgkmcnt(8)
	v_mfma_f32_16x16x32_bf16 v[60:63], v[68:71], v[92:95], v[60:63]
	ds_read_b128 v[190:193], v219 offset:61440
	ds_read_b128 v[166:169], v218 offset:20480
	s_waitcnt lgkmcnt(9)
	v_mfma_f32_16x16x32_bf16 v[56:59], v[68:71], v[158:161], v[56:59]
	ds_read_b128 v[170:173], v218 offset:22528
	s_waitcnt lgkmcnt(9)
	v_mfma_f32_16x16x32_bf16 v[40:43], v[72:75], v[84:87], v[40:43]
	v_mfma_f32_16x16x32_bf16 v[36:39], v[72:75], v[88:91], v[36:39]
	v_mfma_f32_16x16x32_bf16 v[32:35], v[72:75], v[92:95], v[32:35]
	v_mfma_f32_16x16x32_bf16 v[28:31], v[72:75], v[158:161], v[28:31]
	ds_read_b128 v[174:177], v218 offset:24576
	s_waitcnt lgkmcnt(9)
	v_mfma_f32_16x16x32_bf16 v[24:27], v[76:79], v[84:87], v[24:27]
	v_mfma_f32_16x16x32_bf16 v[20:23], v[76:79], v[88:91], v[20:23]
	v_mfma_f32_16x16x32_bf16 v[16:19], v[76:79], v[92:95], v[16:19]
	v_mfma_f32_16x16x32_bf16 v[12:15], v[76:79], v[158:161], v[12:15]
	s_waitcnt lgkmcnt(8)
	v_mfma_f32_16x16x32_bf16 v[8:11], v[80:83], v[84:87], v[8:11]
	v_mfma_f32_16x16x32_bf16 v[4:7], v[80:83], v[88:91], v[4:7]
	v_mfma_f32_16x16x32_bf16 v[0:3], v[80:83], v[92:95], v[0:3]
	v_mfma_f32_16x16x32_bf16 v[48:51], v[80:83], v[158:161], v[48:51]
	s_waitcnt lgkmcnt(6)
	v_mfma_f32_16x16x32_bf16 v[44:47], v[162:165], v[178:181], v[44:47]
	s_waitcnt lgkmcnt(5)
	v_mfma_f32_16x16x32_bf16 v[52:55], v[162:165], v[182:185], v[52:55]
	s_waitcnt lgkmcnt(4)
	v_mfma_f32_16x16x32_bf16 v[60:63], v[162:165], v[186:189], v[60:63]
	s_waitcnt lgkmcnt(3)
	v_mfma_f32_16x16x32_bf16 v[56:59], v[162:165], v[190:193], v[56:59]
	s_waitcnt lgkmcnt(2)
	v_mfma_f32_16x16x32_bf16 v[40:43], v[166:169], v[178:181], v[40:43]
	v_mfma_f32_16x16x32_bf16 v[36:39], v[166:169], v[182:185], v[36:39]
	v_mfma_f32_16x16x32_bf16 v[32:35], v[166:169], v[186:189], v[32:35]
	v_mfma_f32_16x16x32_bf16 v[28:31], v[166:169], v[190:193], v[28:31]
	s_waitcnt lgkmcnt(1)
	v_mfma_f32_16x16x32_bf16 v[24:27], v[170:173], v[178:181], v[24:27]
	v_mfma_f32_16x16x32_bf16 v[20:23], v[170:173], v[182:185], v[20:23]
	v_mfma_f32_16x16x32_bf16 v[16:19], v[170:173], v[186:189], v[16:19]
	v_mfma_f32_16x16x32_bf16 v[12:15], v[170:173], v[190:193], v[12:15]
	s_waitcnt lgkmcnt(0)
	v_mfma_f32_16x16x32_bf16 v[8:11], v[174:177], v[178:181], v[8:11]
	v_mfma_f32_16x16x32_bf16 v[4:7], v[174:177], v[182:185], v[4:7]
	v_mfma_f32_16x16x32_bf16 v[0:3], v[174:177], v[186:189], v[0:3]
	v_mfma_f32_16x16x32_bf16 v[48:51], v[174:177], v[190:193], v[48:51]
	s_waitcnt vmcnt(0)
	s_barrier
	s_add_i32 s9, s9, 1
	s_cmp_lg_u32 s9, 8
	s_cbranch_scc1 .Lg1_loop
	s_or_b32 s52, s49, s6
	s_cmp_gt_u32 s8, 31
	s_mov_b64 s[4:5], -1
	s_cbranch_scc0 .LBB0_220
	s_cmp_lt_u32 s8, 48
	s_cbranch_scc1 .LBB0_221
	s_cmp_lt_u32 s8, 56
	s_cbranch_scc1 .LBB0_225
	s_cmp_lt_u32 s8, 64
	s_cbranch_scc1 .LBB0_233
	s_cmpk_lt_u32 s8, 0x48
	s_cbranch_scc1 .LBB0_546
	s_cmpk_lt_u32 s8, 0x50
	s_cbranch_scc1 .LBB0_547
	s_cmpk_lt_u32 s8, 0x70
	s_cbranch_scc1 .LBB0_548
	s_cmpk_lt_u32 s8, 0x90
	s_cbranch_scc1 .LBB0_549
	s_cmpk_lt_u32 s8, 0x98
	s_cbranch_scc1 .LBB0_550
	s_cmpk_lt_u32 s8, 0xa0
	s_mov_b64 s[6:7], 0
	s_cbranch_scc1 .LBB0_551
	s_cmpk_lt_u32 s8, 0xb0
	s_mov_b64 s[30:31], 0
	s_cbranch_scc1 .LBB0_552
	s_cmpk_eq_i32 s52, 0xb00
	s_cbranch_scc1 .LBB0_553
	s_cmpk_lt_u32 s52, 0xd40
	s_cselect_b64 s[8:9], -1, 0
	s_cmpk_gt_u32 s52, 0xd3f
	s_cselect_b64 s[28:29], -1, 0
	s_mov_b64 s[26:27], 0
	s_branch .LBB0_554

.LBB0_644:
	s_add_i32 s30, s29, s28
	v_lshl_or_b32 v44, s30, 13, v120
	ds_read_u16 v41, v44
	ds_read_u16 v39, v44 offset:128
	ds_read_u16 v38, v44 offset:256
	ds_read_u16 v37, v44 offset:384
	s_add_i32 s29, s30, s53
	s_lshl_b32 s30, s30, 12
	ds_read_u16 v1, v44 offset:512
	ds_read_u16 v0, v44 offset:640
	ds_read_u16 v3, v44 offset:768
	ds_read_u16 v2, v44 offset:896
	ds_read_u16 v5, v44 offset:1024
	ds_read_u16 v4, v44 offset:1152
	ds_read_u16 v7, v44 offset:1280
	ds_read_u16 v6, v44 offset:1408
	ds_read_u16 v9, v44 offset:1536
	ds_read_u16 v8, v44 offset:1664
	ds_read_u16 v11, v44 offset:1792
	s_waitcnt lgkmcnt(10)
	s_movk_i32 s38, 0xeff
	v_lshlrev_b32_e32 v1, 12, v1
	v_bitop3_b32 v1, v1, s38, v106 bitop3:0x36
	v_cmp_ge_u32_e32 vcc, s29, v142
	v_lshl_add_u32 v10, s30, 1, v204
	ds_read_u16 v10, v10
	s_waitcnt lgkmcnt(10)
	s_movk_i32 s38, 0xebf
	v_lshlrev_b32_e32 v0, 12, v0
	v_bitop3_b32 v0, v0, s38, v106 bitop3:0x36
	v_cndmask_b32_e32 v1, 0, v1, vcc
	v_cmp_ge_u32_e32 vcc, s29, v143
	ds_read_u16 v13, v44 offset:2048
	s_waitcnt lgkmcnt(10)
	s_movk_i32 s38, 0xe7f
	v_lshlrev_b32_e32 v3, 12, v3
	v_bitop3_b32 v3, v3, s38, v106 bitop3:0x36
	v_cndmask_b32_e32 v0, 0, v0, vcc
	v_cmp_ge_u32_e32 vcc, s29, v144
	ds_read_u16 v12, v44 offset:2176
	s_waitcnt lgkmcnt(10)
	s_movk_i32 s38, 0xe3f
	v_lshlrev_b32_e32 v2, 12, v2
	v_bitop3_b32 v2, v2, s38, v106 bitop3:0x36
	v_cndmask_b32_e32 v3, 0, v3, vcc
	v_cmp_ge_u32_e32 vcc, s29, v145
	ds_read_u16 v15, v44 offset:2304
	s_waitcnt lgkmcnt(10)
	s_movk_i32 s38, 0xdff
	v_lshlrev_b32_e32 v5, 12, v5
	v_bitop3_b32 v5, v5, s38, v106 bitop3:0x36
	v_cndmask_b32_e32 v2, 0, v2, vcc
	v_cmp_ge_u32_e32 vcc, s29, v146
	ds_read_u16 v14, v44 offset:2432
	s_waitcnt lgkmcnt(10)
	s_movk_i32 s38, 0xdbf
	v_lshlrev_b32_e32 v4, 12, v4
	v_bitop3_b32 v4, v4, s38, v106 bitop3:0x36
	v_cndmask_b32_e32 v5, 0, v5, vcc
	v_cmp_ge_u32_e32 vcc, s29, v147
	ds_read_u16 v17, v44 offset:2560
	s_waitcnt lgkmcnt(10)
	s_movk_i32 s38, 0xd7f
	v_lshlrev_b32_e32 v7, 12, v7
	v_bitop3_b32 v7, v7, s38, v106 bitop3:0x36
	v_cndmask_b32_e32 v4, 0, v4, vcc
	v_cmp_ge_u32_e32 vcc, s29, v148
	ds_read_u16 v16, v44 offset:2688
	s_waitcnt lgkmcnt(10)
	s_movk_i32 s38, 0xd3f
	v_lshlrev_b32_e32 v6, 12, v6
	v_bitop3_b32 v6, v6, s38, v106 bitop3:0x36
	v_cndmask_b32_e32 v7, 0, v7, vcc
	v_cmp_ge_u32_e32 vcc, s29, v149
	ds_read_u16 v19, v44 offset:2816
	s_waitcnt lgkmcnt(10)
	s_movk_i32 s38, 0xcff
	v_lshlrev_b32_e32 v9, 12, v9
	v_bitop3_b32 v9, v9, s38, v106 bitop3:0x36
	v_cndmask_b32_e32 v6, 0, v6, vcc
	v_cmp_ge_u32_e32 vcc, s29, v150
	ds_read_u16 v18, v44 offset:2944
	s_waitcnt lgkmcnt(10)
	s_movk_i32 s38, 0xcbf
	v_lshlrev_b32_e32 v8, 12, v8
	v_bitop3_b32 v8, v8, s38, v106 bitop3:0x36
	v_cndmask_b32_e32 v9, 0, v9, vcc
	v_cmp_ge_u32_e32 vcc, s29, v151
	ds_read_u16 v21, v44 offset:3072
	s_waitcnt lgkmcnt(10)
	s_movk_i32 s38, 0xc7f
	v_lshlrev_b32_e32 v11, 12, v11
	v_bitop3_b32 v11, v11, s38, v106 bitop3:0x36
	v_cndmask_b32_e32 v8, 0, v8, vcc
	v_cmp_ge_u32_e32 vcc, s29, v152
	ds_read_u16 v20, v44 offset:3200
	s_waitcnt lgkmcnt(10)
	v_lshlrev_b32_e32 v10, 12, v10
	v_bitop3_b32 v10, v10, s48, v153 bitop3:0x36
	v_cndmask_b32_e32 v11, 0, v11, vcc
	v_cmp_ge_u32_e32 vcc, s29, v153
	ds_read_u16 v23, v44 offset:3328
	s_waitcnt lgkmcnt(10)
	s_movk_i32 s38, 0xbff
	v_lshlrev_b32_e32 v13, 12, v13
	v_bitop3_b32 v13, v13, s38, v106 bitop3:0x36
	v_cndmask_b32_e32 v10, 0, v10, vcc
	v_cmp_ge_u32_e32 vcc, s29, v154
	ds_read_u16 v22, v44 offset:3456
	s_waitcnt lgkmcnt(10)
	s_movk_i32 s38, 0xbbf
	v_lshlrev_b32_e32 v12, 12, v12
	v_bitop3_b32 v12, v12, s38, v106 bitop3:0x36
	v_cndmask_b32_e32 v13, 0, v13, vcc
	v_cmp_ge_u32_e32 vcc, s29, v155
	ds_read_u16 v25, v44 offset:3584
	s_waitcnt lgkmcnt(10)
	s_movk_i32 s38, 0xb7f
	v_lshlrev_b32_e32 v15, 12, v15
	v_bitop3_b32 v15, v15, s38, v106 bitop3:0x36
	v_cndmask_b32_e32 v12, 0, v12, vcc
	v_cmp_ge_u32_e32 vcc, s29, v156
	ds_read_u16 v24, v44 offset:3712
	s_waitcnt lgkmcnt(10)
	s_movk_i32 s38, 0xb3f
	v_lshlrev_b32_e32 v14, 12, v14
	v_bitop3_b32 v14, v14, s38, v106 bitop3:0x36
	v_cndmask_b32_e32 v15, 0, v15, vcc
	v_cmp_ge_u32_e32 vcc, s29, v157
	ds_read_u16 v27, v44 offset:3840
	s_waitcnt lgkmcnt(10)
	s_movk_i32 s38, 0xaff
	v_lshlrev_b32_e32 v17, 12, v17
	v_bitop3_b32 v17, v17, s38, v106 bitop3:0x36
	v_cndmask_b32_e32 v14, 0, v14, vcc
	v_cmp_ge_u32_e32 vcc, s29, v158
	v_lshl_add_u32 v26, s30, 1, v205
	ds_read_u16 v26, v26
	s_waitcnt lgkmcnt(10)
	s_movk_i32 s38, 0xabf
	v_lshlrev_b32_e32 v16, 12, v16
	v_bitop3_b32 v16, v16, s38, v106 bitop3:0x36
	v_cndmask_b32_e32 v17, 0, v17, vcc
	v_cmp_ge_u32_e32 vcc, s29, v159
	ds_read_u16 v29, v44 offset:4096
	s_waitcnt lgkmcnt(10)
	s_movk_i32 s38, 0xa7f
	v_lshlrev_b32_e32 v19, 12, v19
	v_bitop3_b32 v19, v19, s38, v106 bitop3:0x36
	v_cndmask_b32_e32 v16, 0, v16, vcc
	v_cmp_ge_u32_e32 vcc, s29, v160
	ds_read_u16 v28, v44 offset:4224
	s_waitcnt lgkmcnt(10)
	s_movk_i32 s38, 0xa3f
	v_lshlrev_b32_e32 v18, 12, v18
	v_bitop3_b32 v18, v18, s38, v106 bitop3:0x36
	v_cndmask_b32_e32 v19, 0, v19, vcc
	v_cmp_ge_u32_e32 vcc, s29, v161
	ds_read_u16 v31, v44 offset:4352
	s_waitcnt lgkmcnt(10)
	s_movk_i32 s38, 0x9ff
	v_lshlrev_b32_e32 v21, 12, v21
	v_bitop3_b32 v21, v21, s38, v106 bitop3:0x36
	v_cndmask_b32_e32 v18, 0, v18, vcc
	v_cmp_ge_u32_e32 vcc, s29, v162
	ds_read_u16 v30, v44 offset:4480
	s_waitcnt lgkmcnt(10)
	s_movk_i32 s38, 0x9bf
	v_lshlrev_b32_e32 v20, 12, v20
	v_bitop3_b32 v20, v20, s38, v106 bitop3:0x36
	v_cndmask_b32_e32 v21, 0, v21, vcc
	v_cmp_ge_u32_e32 vcc, s29, v163
	ds_read_u16 v33, v44 offset:4608
	s_waitcnt lgkmcnt(10)
	s_movk_i32 s38, 0x97f
	v_lshlrev_b32_e32 v23, 12, v23
	v_bitop3_b32 v23, v23, s38, v106 bitop3:0x36
	v_cndmask_b32_e32 v20, 0, v20, vcc
	v_cmp_ge_u32_e32 vcc, s29, v166
	ds_read_u16 v32, v44 offset:4736
	s_waitcnt lgkmcnt(10)
	s_movk_i32 s38, 0x93f
	v_lshlrev_b32_e32 v22, 12, v22
	v_bitop3_b32 v22, v22, s38, v106 bitop3:0x36
	v_cndmask_b32_e32 v23, 0, v23, vcc
	v_cmp_ge_u32_e32 vcc, s29, v167
	ds_read_u16 v35, v44 offset:4864
	s_waitcnt lgkmcnt(10)
	s_movk_i32 s38, 0x8ff
	v_lshlrev_b32_e32 v25, 12, v25
	v_bitop3_b32 v25, v25, s38, v106 bitop3:0x36
	v_cndmask_b32_e32 v22, 0, v22, vcc
	v_cmp_ge_u32_e32 vcc, s29, v168
	ds_read_u16 v34, v44 offset:4992
	s_waitcnt lgkmcnt(10)
	s_movk_i32 s38, 0x8bf
	v_lshlrev_b32_e32 v24, 12, v24
	v_bitop3_b32 v24, v24, s38, v106 bitop3:0x36
	v_cndmask_b32_e32 v25, 0, v25, vcc
	v_cmp_ge_u32_e32 vcc, s29, v169
	ds_read_u16 v40, v44 offset:5120
	s_waitcnt lgkmcnt(10)
	s_movk_i32 s38, 0x87f
	v_lshlrev_b32_e32 v27, 12, v27
	v_bitop3_b32 v27, v27, s38, v106 bitop3:0x36
	v_cndmask_b32_e32 v24, 0, v24, vcc
	v_cmp_ge_u32_e32 vcc, s29, v170
	ds_read_u16 v36, v44 offset:5248
	s_waitcnt lgkmcnt(10)
	v_lshlrev_b32_e32 v26, 12, v26
	v_bitop3_b32 v26, v26, s48, v171 bitop3:0x36
	v_cndmask_b32_e32 v27, 0, v27, vcc
	v_cmp_ge_u32_e32 vcc, s29, v171
	ds_read_u16 v43, v44 offset:5376
	s_waitcnt lgkmcnt(10)
	s_movk_i32 s38, 0x7ff
	v_lshlrev_b32_e32 v29, 12, v29
	v_bitop3_b32 v29, v29, s38, v106 bitop3:0x36
	v_cndmask_b32_e32 v26, 0, v26, vcc
	v_cmp_ge_u32_e32 vcc, s29, v172
	ds_read_u16 v42, v44 offset:5504
	s_waitcnt lgkmcnt(10)
	s_movk_i32 s38, 0x7bf
	v_lshlrev_b32_e32 v28, 12, v28
	v_bitop3_b32 v28, v28, s38, v106 bitop3:0x36
	v_cndmask_b32_e32 v29, 0, v29, vcc
	v_cmp_ge_u32_e32 vcc, s29, v173
	ds_read_u16 v46, v44 offset:5632
	s_waitcnt lgkmcnt(10)
	s_movk_i32 s38, 0x77f
	v_lshlrev_b32_e32 v31, 12, v31
	v_bitop3_b32 v31, v31, s38, v106 bitop3:0x36
	v_cndmask_b32_e32 v28, 0, v28, vcc
	v_cmp_ge_u32_e32 vcc, s29, v174
	ds_read_u16 v45, v44 offset:5760
	s_waitcnt lgkmcnt(10)
	s_movk_i32 s38, 0x73f
	v_lshlrev_b32_e32 v30, 12, v30
	v_bitop3_b32 v30, v30, s38, v106 bitop3:0x36
	v_cndmask_b32_e32 v31, 0, v31, vcc
	v_cmp_ge_u32_e32 vcc, s29, v175
	ds_read_u16 v48, v44 offset:5888
	s_waitcnt lgkmcnt(10)
	s_movk_i32 s38, 0x6ff
	v_lshlrev_b32_e32 v33, 12, v33
	v_bitop3_b32 v33, v33, s38, v106 bitop3:0x36
	v_cndmask_b32_e32 v30, 0, v30, vcc
	v_cmp_ge_u32_e32 vcc, s29, v176
	v_lshl_add_u32 v47, s30, 1, v206
	ds_read_u16 v47, v47
	s_waitcnt lgkmcnt(10)
	s_movk_i32 s38, 0x6bf
	v_lshlrev_b32_e32 v32, 12, v32
	v_bitop3_b32 v32, v32, s38, v106 bitop3:0x36
	v_cndmask_b32_e32 v33, 0, v33, vcc
	v_cmp_ge_u32_e32 vcc, s29, v177
	ds_read_u16 v50, v44 offset:6144
	s_waitcnt lgkmcnt(10)
	s_movk_i32 s38, 0x67f
	v_lshlrev_b32_e32 v35, 12, v35
	v_bitop3_b32 v35, v35, s38, v106 bitop3:0x36
	v_cndmask_b32_e32 v32, 0, v32, vcc
	v_cmp_ge_u32_e32 vcc, s29, v178
	ds_read_u16 v49, v44 offset:6272
	s_waitcnt lgkmcnt(10)
	s_movk_i32 s38, 0x63f
	v_lshlrev_b32_e32 v34, 12, v34
	v_bitop3_b32 v34, v34, s38, v106 bitop3:0x36
	v_cndmask_b32_e32 v35, 0, v35, vcc
	v_cmp_ge_u32_e32 vcc, s29, v179
	ds_read_u16 v52, v44 offset:6400
	s_waitcnt lgkmcnt(10)
	s_movk_i32 s38, 0x5ff
	v_lshlrev_b32_e32 v40, 12, v40
	v_bitop3_b32 v40, v40, s38, v106 bitop3:0x36
	v_cndmask_b32_e32 v34, 0, v34, vcc
	v_cmp_ge_u32_e32 vcc, s29, v180
	ds_read_u16 v51, v44 offset:6528
	s_waitcnt lgkmcnt(10)
	s_movk_i32 s38, 0x5bf
	v_lshlrev_b32_e32 v36, 12, v36
	v_bitop3_b32 v36, v36, s38, v106 bitop3:0x36
	v_cndmask_b32_e32 v40, 0, v40, vcc
	v_cmp_ge_u32_e32 vcc, s29, v181
	ds_read_u16 v54, v44 offset:6656
	s_waitcnt lgkmcnt(10)
	s_movk_i32 s38, 0x57f
	v_lshlrev_b32_e32 v43, 12, v43
	v_bitop3_b32 v43, v43, s38, v106 bitop3:0x36
	v_cndmask_b32_e32 v36, 0, v36, vcc
	v_cmp_ge_u32_e32 vcc, s29, v182
	ds_read_u16 v53, v44 offset:6784
	s_waitcnt lgkmcnt(10)
	s_movk_i32 s38, 0x53f
	v_lshlrev_b32_e32 v42, 12, v42
	v_bitop3_b32 v42, v42, s38, v106 bitop3:0x36
	v_cndmask_b32_e32 v43, 0, v43, vcc
	v_cmp_ge_u32_e32 vcc, s29, v183
	ds_read_u16 v56, v44 offset:6912
	s_waitcnt lgkmcnt(10)
	s_movk_i32 s38, 0x4ff
	v_lshlrev_b32_e32 v46, 12, v46
	v_bitop3_b32 v46, v46, s38, v106 bitop3:0x36
	v_cndmask_b32_e32 v42, 0, v42, vcc
	v_cmp_ge_u32_e32 vcc, s29, v184
	ds_read_u16 v55, v44 offset:7040
	s_waitcnt lgkmcnt(10)
	s_movk_i32 s38, 0x4bf
	v_lshlrev_b32_e32 v45, 12, v45
	v_bitop3_b32 v45, v45, s38, v106 bitop3:0x36
	v_cndmask_b32_e32 v46, 0, v46, vcc
	v_cmp_ge_u32_e32 vcc, s29, v185
	ds_read_u16 v58, v44 offset:7168
	s_waitcnt lgkmcnt(10)
	s_movk_i32 s38, 0x47f
	v_lshlrev_b32_e32 v48, 12, v48
	v_bitop3_b32 v48, v48, s38, v106 bitop3:0x36
	v_cndmask_b32_e32 v45, 0, v45, vcc
	v_cmp_ge_u32_e32 vcc, s29, v186
	ds_read_u16 v57, v44 offset:7296
	s_waitcnt lgkmcnt(10)
	v_lshlrev_b32_e32 v47, 12, v47
	v_bitop3_b32 v47, v47, s48, v187 bitop3:0x36
	v_cndmask_b32_e32 v48, 0, v48, vcc
	v_cmp_ge_u32_e32 vcc, s29, v187
	ds_read_u16 v60, v44 offset:7424
	s_waitcnt lgkmcnt(10)
	s_movk_i32 s38, 0x3ff
	v_lshlrev_b32_e32 v50, 12, v50
	v_bitop3_b32 v50, v50, s38, v106 bitop3:0x36
	v_cndmask_b32_e32 v47, 0, v47, vcc
	v_cmp_ge_u32_e32 vcc, s29, v188
	ds_read_u16 v59, v44 offset:7552
	s_waitcnt lgkmcnt(10)
	s_movk_i32 s38, 0x3bf
	v_lshlrev_b32_e32 v49, 12, v49
	v_bitop3_b32 v49, v49, s38, v106 bitop3:0x36
	v_cndmask_b32_e32 v50, 0, v50, vcc
	v_cmp_ge_u32_e32 vcc, s29, v189
	ds_read_u16 v62, v44 offset:7680
	s_waitcnt lgkmcnt(10)
	s_movk_i32 s38, 0x37f
	v_lshlrev_b32_e32 v52, 12, v52
	v_bitop3_b32 v52, v52, s38, v106 bitop3:0x36
	v_cndmask_b32_e32 v49, 0, v49, vcc
	v_cmp_ge_u32_e32 vcc, s29, v190
	ds_read_u16 v61, v44 offset:7808
	s_waitcnt lgkmcnt(10)
	s_movk_i32 s38, 0x33f
	v_lshlrev_b32_e32 v51, 12, v51
	v_bitop3_b32 v51, v51, s38, v106 bitop3:0x36
	v_cndmask_b32_e32 v52, 0, v52, vcc
	v_cmp_ge_u32_e32 vcc, s29, v191
	ds_read_u16 v64, v44 offset:7936
	s_waitcnt lgkmcnt(10)
	s_movk_i32 s38, 0x2ff
	v_lshlrev_b32_e32 v54, 12, v54
	v_bitop3_b32 v54, v54, s38, v106 bitop3:0x36
	v_cndmask_b32_e32 v51, 0, v51, vcc
	v_cmp_ge_u32_e32 vcc, s29, v192
	v_lshl_add_u32 v63, s30, 1, v207
	ds_read_u16 v63, v63
	s_waitcnt lgkmcnt(10)
	s_movk_i32 s38, 0x2bf
	v_lshlrev_b32_e32 v53, 12, v53
	v_bitop3_b32 v53, v53, s38, v106 bitop3:0x36
	v_cndmask_b32_e32 v54, 0, v54, vcc
	v_cmp_ge_u32_e32 vcc, s29, v193
	s_waitcnt lgkmcnt(9)
	s_movk_i32 s38, 0x27f
	v_lshlrev_b32_e32 v56, 12, v56
	v_bitop3_b32 v56, v56, s38, v106 bitop3:0x36
	v_cndmask_b32_e32 v53, 0, v53, vcc
	v_cmp_ge_u32_e32 vcc, s29, v194
	s_waitcnt lgkmcnt(8)
	s_movk_i32 s38, 0x23f
	v_lshlrev_b32_e32 v55, 12, v55
	v_bitop3_b32 v55, v55, s38, v106 bitop3:0x36
	v_cndmask_b32_e32 v56, 0, v56, vcc
	v_cmp_ge_u32_e32 vcc, s29, v195
	s_waitcnt lgkmcnt(7)
	s_movk_i32 s38, 0x1ff
	v_lshlrev_b32_e32 v58, 12, v58
	v_bitop3_b32 v58, v58, s38, v106 bitop3:0x36
	v_cndmask_b32_e32 v55, 0, v55, vcc
	v_cmp_ge_u32_e32 vcc, s29, v196
	s_waitcnt lgkmcnt(6)
	s_movk_i32 s38, 0x1bf
	v_lshlrev_b32_e32 v57, 12, v57
	v_bitop3_b32 v57, v57, s38, v106 bitop3:0x36
	v_cndmask_b32_e32 v58, 0, v58, vcc
	v_cmp_ge_u32_e32 vcc, s29, v197
	s_waitcnt lgkmcnt(5)
	s_movk_i32 s38, 0x17f
	v_lshlrev_b32_e32 v60, 12, v60
	v_bitop3_b32 v60, v60, s38, v106 bitop3:0x36
	v_cndmask_b32_e32 v57, 0, v57, vcc
	v_cmp_ge_u32_e32 vcc, s29, v198
	s_waitcnt lgkmcnt(4)
	s_movk_i32 s38, 0x13f
	v_lshlrev_b32_e32 v59, 12, v59
	v_bitop3_b32 v59, v59, s38, v106 bitop3:0x36
	v_cndmask_b32_e32 v60, 0, v60, vcc
	v_cmp_ge_u32_e32 vcc, s29, v199
	s_waitcnt lgkmcnt(3)
	s_movk_i32 s38, 0xff
	v_lshlrev_b32_e32 v62, 12, v62
	v_bitop3_b32 v62, v62, s38, v106 bitop3:0x36
	v_cndmask_b32_e32 v59, 0, v59, vcc
	v_cmp_ge_u32_e32 vcc, s29, v200
	s_waitcnt lgkmcnt(2)
	s_movk_i32 s38, 0xbf
	v_lshlrev_b32_e32 v61, 12, v61
	v_bitop3_b32 v61, v61, s38, v106 bitop3:0x36
	v_cndmask_b32_e32 v62, 0, v62, vcc
	v_cmp_ge_u32_e32 vcc, s29, v201
	s_waitcnt lgkmcnt(1)
	s_movk_i32 s38, 0x7f
	v_lshlrev_b32_e32 v64, 12, v64
	v_bitop3_b32 v64, v64, s38, v106 bitop3:0x36
	v_cndmask_b32_e32 v61, 0, v61, vcc
	v_cmp_ge_u32_e32 vcc, s29, v202
	s_waitcnt lgkmcnt(0)
	v_lshlrev_b32_e32 v63, 12, v63
	v_bitop3_b32 v63, v63, s48, v203 bitop3:0x36
	v_cndmask_b32_e32 v64, 0, v64, vcc
	v_cmp_ge_u32_e32 vcc, s29, v203
	s_nop 1
	v_cndmask_b32_e32 v63, 0, v63, vcc

.LBB0_912:
	s_or_b64 exec, exec, s[8:9]
	s_lshl_b32 s9, s0, 7
	s_lshl_b32 s0, s21, 7
	v_or_b32_e32 v0, s9, v214
	s_and_b32 s8, s0, 0x380
	s_barrier
	v_readfirstlane_b32 s0, v104
	s_and_b32 s10, s0, 64
	s_lshr_b32 s12, s0, 1
	s_and_b32 s12, s12, 0x7fffffc0
	s_lshr_b32 s0, s0, 6
	s_lshl_b32 s0, s0, 10
	v_bfe_u32 v217, v108, 1, 3
	v_lshlrev_b32_e32 v217, 4, v217
	v_xor_b32_e32 v217, v217, v110
	v_or_b32_e32 v218, s12, v108
	v_lshl_add_u32 v122, v218, 7, v217
	v_xor_b32_e32 v218, 64, v122
	v_or_b32_e32 v219, s10, v108
	v_lshl_add_u32 v109, v219, 7, v217
	v_xor_b32_e32 v219, 64, v109
	v_bfe_u32 v64, v214, 1, 3
	v_and_b32_e32 v65, 7, v104
	v_xor_b32_e32 v64, v64, v65
	v_lshlrev_b32_e32 v64, 4, v64
	v_lshl_add_u32 v64, v214, 11, v64
	v_add_u32_e32 v65, 0x10000, v64
	v_add_u32_e32 v66, 0x20000, v64
	v_add_u32_e32 v67, 0x30000, v64
	v_readlane_b32 s10, v250, 36
	v_readlane_b32 s11, v250, 37
	v_readlane_b32 s22, v249, 4
	v_readlane_b32 s23, v249, 5
	s_lshl_b32 s12, s9, 11
	s_add_u32 s10, s10, s12
	s_addc_u32 s11, s11, 0
	s_lshl_b32 s12, s8, 11
	s_add_u32 s22, s22, s12
	s_addc_u32 s23, s23, 0
	s_add_u32 m0, s0, 0x0
	s_nop 0
	global_load_lds_dwordx4 v64, s[10:11]
	s_add_u32 m0, s0, 0x1000
	s_nop 0
	global_load_lds_dwordx4 v65, s[10:11]
	s_add_u32 m0, s0, 0x2000
	s_nop 0
	global_load_lds_dwordx4 v66, s[10:11]
	s_add_u32 m0, s0, 0x3000
	s_nop 0
	global_load_lds_dwordx4 v67, s[10:11]
	s_add_u32 m0, s0, 0x9000
	s_nop 0
	global_load_lds_dwordx4 v64, s[22:23]
	s_add_u32 m0, s0, 0xa000
	s_nop 0
	global_load_lds_dwordx4 v65, s[22:23]
	s_add_u32 m0, s0, 0xb000
	s_nop 0
	global_load_lds_dwordx4 v66, s[22:23]
	s_add_u32 m0, s0, 0xc000
	s_nop 0
	global_load_lds_dwordx4 v67, s[22:23]
	s_add_u32 s10, s10, 0x80
	s_addc_u32 s11, s11, 0
	s_add_u32 s22, s22, 0x80
	s_addc_u32 s23, s23, 0
	v_mov_b64_e32 v[0:1], 0
	v_mov_b64_e32 v[2:3], 0
	v_mov_b64_e32 v[4:5], 0
	v_mov_b64_e32 v[6:7], 0
	v_mov_b64_e32 v[8:9], 0
	v_mov_b64_e32 v[10:11], 0
	v_mov_b64_e32 v[12:13], 0
	v_mov_b64_e32 v[14:15], 0
	v_mov_b64_e32 v[16:17], 0
	v_mov_b64_e32 v[18:19], 0
	v_mov_b64_e32 v[20:21], 0
	v_mov_b64_e32 v[22:23], 0
	v_mov_b64_e32 v[24:25], 0
	v_mov_b64_e32 v[26:27], 0
	v_mov_b64_e32 v[28:29], 0
	v_mov_b64_e32 v[30:31], 0
	v_mov_b64_e32 v[32:33], 0
	v_mov_b64_e32 v[34:35], 0
	v_mov_b64_e32 v[36:37], 0
	v_mov_b64_e32 v[38:39], 0
	v_mov_b64_e32 v[40:41], 0
	v_mov_b64_e32 v[42:43], 0
	v_mov_b64_e32 v[44:45], 0
	v_mov_b64_e32 v[46:47], 0
	v_mov_b64_e32 v[48:49], 0
	v_mov_b64_e32 v[50:51], 0
	v_mov_b64_e32 v[52:53], 0
	v_mov_b64_e32 v[54:55], 0
	v_mov_b64_e32 v[56:57], 0
	v_mov_b64_e32 v[58:59], 0
	v_mov_b64_e32 v[60:61], 0
	v_mov_b64_e32 v[62:63], 0
	s_mov_b32 s21, 0
	s_waitcnt vmcnt(0)
	s_barrier
.Lg4_loop:
	s_add_u32 m0, s0, 0x4800
	s_nop 0
	global_load_lds_dwordx4 v64, s[10:11]
	s_add_u32 m0, s0, 0x5800
	s_nop 0
	global_load_lds_dwordx4 v65, s[10:11]
	s_add_u32 m0, s0, 0x6800
	s_nop 0
	global_load_lds_dwordx4 v66, s[10:11]
	s_add_u32 m0, s0, 0x7800
	s_nop 0
	global_load_lds_dwordx4 v67, s[10:11]
	s_add_u32 m0, s0, 0xd800
	s_nop 0
	global_load_lds_dwordx4 v64, s[22:23]
	s_add_u32 m0, s0, 0xe800
	s_nop 0
	global_load_lds_dwordx4 v65, s[22:23]
	s_add_u32 m0, s0, 0xf800
	s_nop 0
	global_load_lds_dwordx4 v66, s[22:23]
	s_add_u32 m0, s0, 0x10800
	s_nop 0
	global_load_lds_dwordx4 v67, s[22:23]
	s_add_u32 s10, s10, 0x80
	s_addc_u32 s11, s11, 0
	s_add_u32 s22, s22, 0x80
	s_addc_u32 s23, s23, 0
	ds_read_b128 v[68:71], v122 offset:0
	ds_read_b128 v[84:87], v109 offset:36864
	ds_read_b128 v[88:91], v109 offset:38912
	ds_read_b128 v[92:95], v109 offset:40960
	ds_read_b128 v[130:133], v109 offset:43008
	ds_read_b128 v[72:75], v122 offset:2048
	ds_read_b128 v[76:79], v122 offset:4096
	ds_read_b128 v[80:83], v122 offset:6144
	s_waitcnt lgkmcnt(6)
	v_mfma_f32_16x16x32_bf16 v[12:15], v[68:71], v[84:87], v[12:15]
	ds_read_b128 v[134:137], v218 offset:0
	ds_read_b128 v[150:153], v219 offset:36864
	s_waitcnt lgkmcnt(7)
	v_mfma_f32_16x16x32_bf16 v[32:35], v[68:71], v[88:91], v[32:35]
	ds_read_b128 v[154:157], v219 offset:38912
	ds_read_b128 v[170:173], v219 offset:40960
	s_waitcnt lgkmcnt(8)
	v_mfma_f32_16x16x32_bf16 v[52:55], v[68:71], v[92:95], v[52:55]
	ds_read_b128 v[174:177], v219 offset:43008
	ds_read_b128 v[138:141], v218 offset:2048
	s_waitcnt lgkmcnt(9)
	v_mfma_f32_16x16x32_bf16 v[56:59], v[68:71], v[130:133], v[56:59]
	ds_read_b128 v[142:145], v218 offset:4096
	s_waitcnt lgkmcnt(9)
	v_mfma_f32_16x16x32_bf16 v[36:39], v[72:75], v[84:87], v[36:39]
	v_mfma_f32_16x16x32_bf16 v[40:43], v[72:75], v[88:91], v[40:43]
	v_mfma_f32_16x16x32_bf16 v[44:47], v[72:75], v[92:95], v[44:47]
	v_mfma_f32_16x16x32_bf16 v[48:51], v[72:75], v[130:133], v[48:51]
	ds_read_b128 v[146:149], v218 offset:6144
	s_waitcnt lgkmcnt(9)
	v_mfma_f32_16x16x32_bf16 v[24:27], v[76:79], v[84:87], v[24:27]
	v_mfma_f32_16x16x32_bf16 v[20:23], v[76:79], v[88:91], v[20:23]
	v_mfma_f32_16x16x32_bf16 v[16:19], v[76:79], v[92:95], v[16:19]
	v_mfma_f32_16x16x32_bf16 v[28:31], v[76:79], v[130:133], v[28:31]
	s_waitcnt lgkmcnt(8)
	v_mfma_f32_16x16x32_bf16 v[0:3], v[80:83], v[84:87], v[0:3]
	v_mfma_f32_16x16x32_bf16 v[4:7], v[80:83], v[88:91], v[4:7]
	v_mfma_f32_16x16x32_bf16 v[8:11], v[80:83], v[92:95], v[8:11]
	v_mfma_f32_16x16x32_bf16 v[60:63], v[80:83], v[130:133], v[60:63]
	s_waitcnt lgkmcnt(6)
	v_mfma_f32_16x16x32_bf16 v[12:15], v[134:137], v[150:153], v[12:15]
	s_waitcnt lgkmcnt(5)
	v_mfma_f32_16x16x32_bf16 v[32:35], v[134:137], v[154:157], v[32:35]
	s_waitcnt lgkmcnt(4)
	v_mfma_f32_16x16x32_bf16 v[52:55], v[134:137], v[170:173], v[52:55]
	s_waitcnt lgkmcnt(3)
	v_mfma_f32_16x16x32_bf16 v[56:59], v[134:137], v[174:177], v[56:59]
	s_waitcnt lgkmcnt(2)
	v_mfma_f32_16x16x32_bf16 v[36:39], v[138:141], v[150:153], v[36:39]
	v_mfma_f32_16x16x32_bf16 v[40:43], v[138:141], v[154:157], v[40:43]
	v_mfma_f32_16x16x32_bf16 v[44:47], v[138:141], v[170:173], v[44:47]
	v_mfma_f32_16x16x32_bf16 v[48:51], v[138:141], v[174:177], v[48:51]
	s_waitcnt lgkmcnt(1)
	v_mfma_f32_16x16x32_bf16 v[24:27], v[142:145], v[150:153], v[24:27]
	v_mfma_f32_16x16x32_bf16 v[20:23], v[142:145], v[154:157], v[20:23]
	v_mfma_f32_16x16x32_bf16 v[16:19], v[142:145], v[170:173], v[16:19]
	v_mfma_f32_16x16x32_bf16 v[28:31], v[142:145], v[174:177], v[28:31]
	s_waitcnt lgkmcnt(0)
	v_mfma_f32_16x16x32_bf16 v[0:3], v[146:149], v[150:153], v[0:3]
	v_mfma_f32_16x16x32_bf16 v[4:7], v[146:149], v[154:157], v[4:7]
	v_mfma_f32_16x16x32_bf16 v[8:11], v[146:149], v[170:173], v[8:11]
	v_mfma_f32_16x16x32_bf16 v[60:63], v[146:149], v[174:177], v[60:63]
	s_waitcnt vmcnt(0)
	s_barrier
	s_cmp_eq_u32 s21, 7
	s_cbranch_scc1 .Lg4_skip
	s_add_u32 m0, s0, 0x0
	s_nop 0
	global_load_lds_dwordx4 v64, s[10:11]
	s_add_u32 m0, s0, 0x1000
	s_nop 0
	global_load_lds_dwordx4 v65, s[10:11]
	s_add_u32 m0, s0, 0x2000
	s_nop 0
	global_load_lds_dwordx4 v66, s[10:11]
	s_add_u32 m0, s0, 0x3000
	s_nop 0
	global_load_lds_dwordx4 v67, s[10:11]
	s_add_u32 m0, s0, 0x9000
	s_nop 0
	global_load_lds_dwordx4 v64, s[22:23]
	s_add_u32 m0, s0, 0xa000
	s_nop 0
	global_load_lds_dwordx4 v65, s[22:23]
	s_add_u32 m0, s0, 0xb000
	s_nop 0
	global_load_lds_dwordx4 v66, s[22:23]
	s_add_u32 m0, s0, 0xc000
	s_nop 0
	global_load_lds_dwordx4 v67, s[22:23]
	s_add_u32 s10, s10, 0x80
	s_addc_u32 s11, s11, 0
	s_add_u32 s22, s22, 0x80
	s_addc_u32 s23, s23, 0
.Lg4_skip:
	ds_read_b128 v[68:71], v122 offset:18432
	ds_read_b128 v[84:87], v109 offset:55296
	ds_read_b128 v[88:91], v109 offset:57344
	ds_read_b128 v[92:95], v109 offset:59392
	ds_read_b128 v[130:133], v109 offset:61440
	ds_read_b128 v[72:75], v122 offset:20480
	ds_read_b128 v[76:79], v122 offset:22528
	ds_read_b128 v[80:83], v122 offset:24576
	s_waitcnt lgkmcnt(6)
	v_mfma_f32_16x16x32_bf16 v[12:15], v[68:71], v[84:87], v[12:15]
	ds_read_b128 v[134:137], v218 offset:18432
	ds_read_b128 v[150:153], v219 offset:55296
	s_waitcnt lgkmcnt(7)
	v_mfma_f32_16x16x32_bf16 v[32:35], v[68:71], v[88:91], v[32:35]
	ds_read_b128 v[154:157], v219 offset:57344
	ds_read_b128 v[170:173], v219 offset:59392
	s_waitcnt lgkmcnt(8)
	v_mfma_f32_16x16x32_bf16 v[52:55], v[68:71], v[92:95], v[52:55]
	ds_read_b128 v[174:177], v219 offset:61440
	ds_read_b128 v[138:141], v218 offset:20480
	s_waitcnt lgkmcnt(9)
	v_mfma_f32_16x16x32_bf16 v[56:59], v[68:71], v[130:133], v[56:59]
	ds_read_b128 v[142:145], v218 offset:22528
	s_waitcnt lgkmcnt(9)
	v_mfma_f32_16x16x32_bf16 v[36:39], v[72:75], v[84:87], v[36:39]
	v_mfma_f32_16x16x32_bf16 v[40:43], v[72:75], v[88:91], v[40:43]
	v_mfma_f32_16x16x32_bf16 v[44:47], v[72:75], v[92:95], v[44:47]
	v_mfma_f32_16x16x32_bf16 v[48:51], v[72:75], v[130:133], v[48:51]
	ds_read_b128 v[146:149], v218 offset:24576
	s_waitcnt lgkmcnt(9)
	v_mfma_f32_16x16x32_bf16 v[24:27], v[76:79], v[84:87], v[24:27]
	v_mfma_f32_16x16x32_bf16 v[20:23], v[76:79], v[88:91], v[20:23]
	v_mfma_f32_16x16x32_bf16 v[16:19], v[76:79], v[92:95], v[16:19]
	v_mfma_f32_16x16x32_bf16 v[28:31], v[76:79], v[130:133], v[28:31]
	s_waitcnt lgkmcnt(8)
	v_mfma_f32_16x16x32_bf16 v[0:3], v[80:83], v[84:87], v[0:3]
	v_mfma_f32_16x16x32_bf16 v[4:7], v[80:83], v[88:91], v[4:7]
	v_mfma_f32_16x16x32_bf16 v[8:11], v[80:83], v[92:95], v[8:11]
	v_mfma_f32_16x16x32_bf16 v[60:63], v[80:83], v[130:133], v[60:63]
	s_waitcnt lgkmcnt(6)
	v_mfma_f32_16x16x32_bf16 v[12:15], v[134:137], v[150:153], v[12:15]
	s_waitcnt lgkmcnt(5)
	v_mfma_f32_16x16x32_bf16 v[32:35], v[134:137], v[154:157], v[32:35]
	s_waitcnt lgkmcnt(4)
	v_mfma_f32_16x16x32_bf16 v[52:55], v[134:137], v[170:173], v[52:55]
	s_waitcnt lgkmcnt(3)
	v_mfma_f32_16x16x32_bf16 v[56:59], v[134:137], v[174:177], v[56:59]
	s_waitcnt lgkmcnt(2)
	v_mfma_f32_16x16x32_bf16 v[36:39], v[138:141], v[150:153], v[36:39]
	v_mfma_f32_16x16x32_bf16 v[40:43], v[138:141], v[154:157], v[40:43]
	v_mfma_f32_16x16x32_bf16 v[44:47], v[138:141], v[170:173], v[44:47]
	v_mfma_f32_16x16x32_bf16 v[48:51], v[138:141], v[174:177], v[48:51]
	s_waitcnt lgkmcnt(1)
	v_mfma_f32_16x16x32_bf16 v[24:27], v[142:145], v[150:153], v[24:27]
	v_mfma_f32_16x16x32_bf16 v[20:23], v[142:145], v[154:157], v[20:23]
	v_mfma_f32_16x16x32_bf16 v[16:19], v[142:145], v[170:173], v[16:19]
	v_mfma_f32_16x16x32_bf16 v[28:31], v[142:145], v[174:177], v[28:31]
	s_waitcnt lgkmcnt(0)
	v_mfma_f32_16x16x32_bf16 v[0:3], v[146:149], v[150:153], v[0:3]
	v_mfma_f32_16x16x32_bf16 v[4:7], v[146:149], v[154:157], v[4:7]
	v_mfma_f32_16x16x32_bf16 v[8:11], v[146:149], v[170:173], v[8:11]
	v_mfma_f32_16x16x32_bf16 v[60:63], v[146:149], v[174:177], v[60:63]
	s_waitcnt vmcnt(0)
	s_barrier
	s_add_i32 s21, s21, 1
	s_cmp_lg_u32 s21, 8
	s_cbranch_scc1 .Lg4_loop
	v_readfirstlane_b32 s0, v104
	s_and_b32 s10, s0, 64
	s_lshr_b32 s0, s0, 1
	s_and_b32 s12, s0, 0x7fffffc0
	s_lshl_b32 s0, s8, 2
	s_add_u32 s8, s36, s0
	s_waitcnt vmcnt(6)
	v_or_b32_e32 v64, s9, v112
	s_addc_u32 s9, s37, 0
	s_lshl_b32 s10, s10, 2
	s_add_u32 s8, s8, s10
	v_add_u32_e32 v116, s12, v64
	s_addc_u32 s9, s9, 0
	v_mov_b32_e32 v115, v117
	v_lshl_add_u64 v[64:65], s[8:9], 0, v[114:115]
	v_lshlrev_b64 v[66:67], 12, v[116:117]
	v_lshl_add_u64 v[68:69], v[64:65], 0, v[66:67]
	v_or_b32_e32 v70, 0x1000, v66
	v_mov_b32_e32 v71, v67
	s_waitcnt vmcnt(5)
	v_lshl_add_u64 v[72:73], v[64:65], 0, v[70:71]
	global_load_dword v106, v[68:69], off
	global_load_dword v107, v[68:69], off offset:64
	global_load_dword v109, v[68:69], off offset:128
	global_load_dword v111, v[68:69], off offset:192
	global_load_dword v113, v[72:73], off
	global_load_dword v116, v[72:73], off offset:64
	global_load_dword v118, v[72:73], off offset:128
	global_load_dword v119, v[72:73], off offset:192
	v_or_b32_e32 v68, 0x2000, v66
	v_mov_b32_e32 v69, v67
	v_lshl_add_u64 v[72:73], v[64:65], 0, v[68:69]
	v_or_b32_e32 v74, 0x3000, v66
	v_mov_b32_e32 v75, v67
	s_waitcnt vmcnt(9)
	v_lshl_add_u64 v[76:77], v[64:65], 0, v[74:75]
	global_load_dword v120, v[72:73], off
	global_load_dword v121, v[72:73], off offset:64
	global_load_dword v122, v[72:73], off offset:128
	global_load_dword v123, v[72:73], off offset:192
	global_load_dword v124, v[76:77], off
	global_load_dword v125, v[76:77], off offset:64
	global_load_dword v126, v[76:77], off offset:128
	global_load_dword v127, v[76:77], off offset:192
	v_or_b32_e32 v72, 0x10000, v66
	v_mov_b32_e32 v73, v67
	v_lshl_add_u64 v[76:77], v[64:65], 0, v[72:73]
	v_or_b32_e32 v78, 0x11000, v66
	v_mov_b32_e32 v79, v67
	v_lshl_add_u64 v[80:81], v[64:65], 0, v[78:79]
	global_load_dword v128, v[76:77], off
	global_load_dword v129, v[76:77], off offset:64
	global_load_dword v130, v[76:77], off offset:128
	global_load_dword v131, v[76:77], off offset:192
	global_load_dword v132, v[80:81], off
	global_load_dword v133, v[80:81], off offset:64
	global_load_dword v134, v[80:81], off offset:128
	global_load_dword v135, v[80:81], off offset:192
	v_or_b32_e32 v76, 0x12000, v66
	v_mov_b32_e32 v77, v67
	v_lshl_add_u64 v[80:81], v[64:65], 0, v[76:77]
	v_or_b32_e32 v82, 0x13000, v66
	v_mov_b32_e32 v83, v67
	v_lshl_add_u64 v[84:85], v[64:65], 0, v[82:83]
	global_load_dword v136, v[80:81], off
	global_load_dword v137, v[80:81], off offset:64
	global_load_dword v138, v[80:81], off offset:128
	global_load_dword v139, v[80:81], off offset:192
	global_load_dword v140, v[84:85], off
	global_load_dword v141, v[84:85], off offset:64
	global_load_dword v142, v[84:85], off offset:128
	global_load_dword v143, v[84:85], off offset:192
	v_or_b32_e32 v80, 0x20000, v66
	v_mov_b32_e32 v81, v67
	v_lshl_add_u64 v[84:85], v[64:65], 0, v[80:81]
	v_or_b32_e32 v86, 0x21000, v66
	v_mov_b32_e32 v87, v67
	v_lshl_add_u64 v[88:89], v[64:65], 0, v[86:87]
	global_load_dword v144, v[84:85], off
	global_load_dword v145, v[84:85], off offset:64
	global_load_dword v146, v[84:85], off offset:128
	global_load_dword v147, v[84:85], off offset:192
	global_load_dword v148, v[88:89], off
	global_load_dword v149, v[88:89], off offset:64
	global_load_dword v150, v[88:89], off offset:128
	global_load_dword v151, v[88:89], off offset:192
	v_or_b32_e32 v84, 0x22000, v66
	v_mov_b32_e32 v85, v67
	v_lshl_add_u64 v[88:89], v[64:65], 0, v[84:85]
	v_or_b32_e32 v90, 0x23000, v66
	v_mov_b32_e32 v91, v67
	s_waitcnt vmcnt(40)
	v_lshl_add_u64 v[92:93], v[64:65], 0, v[90:91]
	global_load_dword v152, v[88:89], off
	global_load_dword v153, v[88:89], off offset:64
	global_load_dword v154, v[88:89], off offset:128
	global_load_dword v155, v[88:89], off offset:192
	global_load_dword v156, v[92:93], off
	global_load_dword v157, v[92:93], off offset:64
	global_load_dword v158, v[92:93], off offset:128
	global_load_dword v159, v[92:93], off offset:192
	v_or_b32_e32 v88, 0x30000, v66
	v_mov_b32_e32 v89, v67
	v_lshl_add_u64 v[92:93], v[64:65], 0, v[88:89]
	v_or_b32_e32 v94, 0x31000, v66
	v_mov_b32_e32 v95, v67
	v_lshl_add_u64 v[100:101], v[64:65], 0, v[94:95]
	global_load_dword v160, v[92:93], off
	global_load_dword v161, v[92:93], off offset:64
	global_load_dword v162, v[92:93], off offset:128
	global_load_dword v163, v[92:93], off offset:192
	global_load_dword v164, v[100:101], off
	global_load_dword v165, v[100:101], off offset:64
	global_load_dword v166, v[100:101], off offset:128
	global_load_dword v167, v[100:101], off offset:192
	v_or_b32_e32 v92, 0x32000, v66
	v_mov_b32_e32 v93, v67
	v_lshl_add_u64 v[100:101], v[64:65], 0, v[92:93]
	v_or_b32_e32 v102, 0x33000, v66
	v_mov_b32_e32 v103, v67
	v_lshl_add_u64 v[64:65], v[64:65], 0, v[102:103]
	global_load_dword v168, v[100:101], off
	global_load_dword v169, v[100:101], off offset:64
	global_load_dword v170, v[100:101], off offset:128
	s_nop 0
	global_load_dword v100, v[100:101], off offset:192
	s_nop 0
	global_load_dword v101, v[64:65], off
	global_load_dword v171, v[64:65], off offset:64
	global_load_dword v172, v[64:65], off offset:128
	global_load_dword v173, v[64:65], off offset:192
	s_add_u32 s0, s52, s0
	s_addc_u32 s9, s53, 0
	s_add_u32 s8, s0, s10
	s_addc_u32 s9, s9, 0
	v_lshl_add_u64 v[64:65], s[8:9], 0, v[114:115]
	v_lshl_add_u64 v[66:67], v[64:65], 0, v[66:67]
	s_waitcnt vmcnt(62)
	v_add_f32_e32 v12, v12, v106
	global_store_dword v[66:67], v12, off
	v_add_f32_e32 v12, v32, v107
	global_store_dword v[66:67], v12, off offset:64
	s_waitcnt vmcnt(62)
	v_add_f32_e32 v12, v52, v109
	global_store_dword v[66:67], v12, off offset:128
	v_add_f32_e32 v12, v56, v111
	global_store_dword v[66:67], v12, off offset:192
	v_lshl_add_u64 v[66:67], v[64:65], 0, v[70:71]
	s_waitcnt vmcnt(62)
	v_add_f32_e32 v12, v13, v113
	global_store_dword v[66:67], v12, off
	v_add_f32_e32 v12, v33, v116
	global_store_dword v[66:67], v12, off offset:64
	s_waitcnt vmcnt(62)
	v_add_f32_e32 v12, v53, v118
	global_store_dword v[66:67], v12, off offset:128
	v_add_f32_e32 v12, v57, v119
	global_store_dword v[66:67], v12, off offset:192
	v_lshl_add_u64 v[12:13], v[64:65], 0, v[68:69]
	s_waitcnt vmcnt(62)
	v_add_f32_e32 v14, v14, v120
	global_store_dword v[12:13], v14, off
	v_add_f32_e32 v14, v34, v121
	global_store_dword v[12:13], v14, off offset:64
	s_waitcnt vmcnt(62)
	v_add_f32_e32 v14, v54, v122
	global_store_dword v[12:13], v14, off offset:128
	v_add_f32_e32 v14, v58, v123
	global_store_dword v[12:13], v14, off offset:192
	v_lshl_add_u64 v[12:13], v[64:65], 0, v[74:75]
	s_waitcnt vmcnt(62)
	v_add_f32_e32 v14, v15, v124
	global_store_dword v[12:13], v14, off
	v_add_f32_e32 v14, v35, v125
	global_store_dword v[12:13], v14, off offset:64
	s_waitcnt vmcnt(62)
	v_add_f32_e32 v14, v55, v126
	global_store_dword v[12:13], v14, off offset:128
	v_add_f32_e32 v14, v59, v127
	global_store_dword v[12:13], v14, off offset:192
	v_lshl_add_u64 v[12:13], v[64:65], 0, v[72:73]
	s_waitcnt vmcnt(62)
	v_add_f32_e32 v14, v36, v128
	global_store_dword v[12:13], v14, off
	v_add_f32_e32 v14, v40, v129
	global_store_dword v[12:13], v14, off offset:64
	s_waitcnt vmcnt(62)
	v_add_f32_e32 v14, v44, v130
	global_store_dword v[12:13], v14, off offset:128
	v_add_f32_e32 v14, v48, v131
	global_store_dword v[12:13], v14, off offset:192
	v_lshl_add_u64 v[12:13], v[64:65], 0, v[78:79]
	s_waitcnt vmcnt(62)
	v_add_f32_e32 v14, v37, v132
	global_store_dword v[12:13], v14, off
	v_add_f32_e32 v14, v41, v133
	global_store_dword v[12:13], v14, off offset:64
	s_waitcnt vmcnt(62)
	v_add_f32_e32 v14, v45, v134
	global_store_dword v[12:13], v14, off offset:128
	v_add_f32_e32 v14, v49, v135
	global_store_dword v[12:13], v14, off offset:192
	v_lshl_add_u64 v[12:13], v[64:65], 0, v[76:77]
	s_waitcnt vmcnt(62)
	v_add_f32_e32 v14, v38, v136
	global_store_dword v[12:13], v14, off
	v_add_f32_e32 v14, v42, v137
	global_store_dword v[12:13], v14, off offset:64
	s_waitcnt vmcnt(62)
	v_add_f32_e32 v14, v46, v138
	global_store_dword v[12:13], v14, off offset:128
	v_add_f32_e32 v14, v50, v139
	global_store_dword v[12:13], v14, off offset:192
	v_lshl_add_u64 v[12:13], v[64:65], 0, v[82:83]
	s_waitcnt vmcnt(62)
	v_add_f32_e32 v14, v39, v140
	global_store_dword v[12:13], v14, off
	v_add_f32_e32 v14, v43, v141
	global_store_dword v[12:13], v14, off offset:64
	s_waitcnt vmcnt(62)
	v_add_f32_e32 v14, v47, v142
	global_store_dword v[12:13], v14, off offset:128
	v_add_f32_e32 v14, v51, v143
	global_store_dword v[12:13], v14, off offset:192
	v_lshl_add_u64 v[12:13], v[64:65], 0, v[80:81]
	s_waitcnt vmcnt(62)
	v_add_f32_e32 v14, v24, v144
	global_store_dword v[12:13], v14, off
	v_add_f32_e32 v14, v20, v145
	global_store_dword v[12:13], v14, off offset:64
	s_waitcnt vmcnt(62)
	v_add_f32_e32 v14, v16, v146
	global_store_dword v[12:13], v14, off offset:128
	v_add_f32_e32 v14, v28, v147
	global_store_dword v[12:13], v14, off offset:192
	v_lshl_add_u64 v[12:13], v[64:65], 0, v[86:87]
	s_waitcnt vmcnt(62)
	v_add_f32_e32 v14, v25, v148
	global_store_dword v[12:13], v14, off
	v_add_f32_e32 v14, v21, v149
	global_store_dword v[12:13], v14, off offset:64
	s_waitcnt vmcnt(62)
	v_add_f32_e32 v14, v17, v150
	global_store_dword v[12:13], v14, off offset:128
	v_add_f32_e32 v14, v29, v151
	global_store_dword v[12:13], v14, off offset:192
	v_lshl_add_u64 v[12:13], v[64:65], 0, v[84:85]
	s_waitcnt vmcnt(62)
	v_add_f32_e32 v14, v26, v152
	global_store_dword v[12:13], v14, off
	v_add_f32_e32 v14, v22, v153
	global_store_dword v[12:13], v14, off offset:64
	s_waitcnt vmcnt(62)
	v_add_f32_e32 v14, v18, v154
	global_store_dword v[12:13], v14, off offset:128
	v_add_f32_e32 v14, v30, v155
	global_store_dword v[12:13], v14, off offset:192
	v_lshl_add_u64 v[12:13], v[64:65], 0, v[90:91]
	s_waitcnt vmcnt(62)
	v_add_f32_e32 v14, v27, v156
	global_store_dword v[12:13], v14, off
	v_add_f32_e32 v14, v23, v157
	global_store_dword v[12:13], v14, off offset:64
	s_waitcnt vmcnt(62)
	v_add_f32_e32 v14, v19, v158
	global_store_dword v[12:13], v14, off offset:128
	v_add_f32_e32 v14, v31, v159
	global_store_dword v[12:13], v14, off offset:192
	v_lshl_add_u64 v[12:13], v[64:65], 0, v[88:89]
	s_waitcnt vmcnt(62)
	v_add_f32_e32 v0, v0, v160
	global_store_dword v[12:13], v0, off
	v_add_f32_e32 v0, v4, v161
	global_store_dword v[12:13], v0, off offset:64
	s_waitcnt vmcnt(62)
	v_add_f32_e32 v0, v8, v162
	global_store_dword v[12:13], v0, off offset:128
	v_add_f32_e32 v0, v60, v163
	global_store_dword v[12:13], v0, off offset:192
	v_lshl_add_u64 v[12:13], v[64:65], 0, v[94:95]
	s_waitcnt vmcnt(62)
	v_add_f32_e32 v0, v1, v164
	global_store_dword v[12:13], v0, off
	v_add_f32_e32 v0, v5, v165
	global_store_dword v[12:13], v0, off offset:64
	s_waitcnt vmcnt(62)
	v_add_f32_e32 v0, v9, v166
	global_store_dword v[12:13], v0, off offset:128
	v_add_f32_e32 v0, v61, v167
	global_store_dword v[12:13], v0, off offset:192
	v_lshl_add_u64 v[0:1], v[64:65], 0, v[92:93]
	s_waitcnt vmcnt(62)
	v_add_f32_e32 v2, v2, v168
	global_store_dword v[0:1], v2, off
	v_add_f32_e32 v2, v6, v169
	global_store_dword v[0:1], v2, off offset:64
	s_waitcnt vmcnt(62)
	v_add_f32_e32 v2, v10, v170
	global_store_dword v[0:1], v2, off offset:128
	v_add_f32_e32 v2, v62, v100
	global_store_dword v[0:1], v2, off offset:192
	v_lshl_add_u64 v[0:1], v[64:65], 0, v[102:103]
	s_waitcnt vmcnt(62)
	v_add_f32_e32 v2, v3, v101
	global_store_dword v[0:1], v2, off
	v_add_f32_e32 v2, v7, v171
	global_store_dword v[0:1], v2, off offset:64
	s_waitcnt vmcnt(62)
	v_add_f32_e32 v2, v11, v172
	global_store_dword v[0:1], v2, off offset:128
	v_add_f32_e32 v2, v63, v173
	global_store_dword v[0:1], v2, off offset:192
	s_branch .LBB0_892
